# rs phases: each workgroup recomputes rs only for the two row tiles its in-projection tiles read; the three grid barriers behind them removed
# baseline (speedup 1.0000x reference)
; DI int launder(int x) { asm volatile("" : "+v"(x)); return x; }
; DI void rs_phase(const float* PS, float* RS, int G, int blk) {
;     for (int row = blk * NTHREADS + launder((int)threadIdx.x); row < M; row += G * NTHREADS) {
;         const f32x4* p = (const f32x4*)(PS + (size_t)row * 32); float s = 0.f;
; #pragma unroll
;         for (int j = 0; j < 8; ++j) { const f32x4 v = p[j]; s += (v.x + v.y) + (v.z + v.w); }
;         RS[row] = rsqrtf(s * (1.f / 2048.f) + 1e-6f);
;     }
; }
.LBB0_419:
	s_cmp_lt_i32 s90, 5
	s_cselect_b64 s[0:1], -1, 0
	s_and_b64 s[2:3], s[0:1], s[2:3]
	s_andn2_b64 vcc, exec, s[2:3]
	s_cbranch_vccnz .LBB0_424
	v_mov_b32_e32 v0, v196
	s_and_b32 s0, s89, 7
	s_lshl_b32 s0, s0, 4
	s_bfe_u32 vcc_lo, s89, 0x30003
	s_add_i32 s0, s0, vcc_lo
	s_lshl_b32 s0, s0, 8
	v_lshrrev_b32_e32 v1, 8, v0
	v_and_b32_e32 v0, 0xff, v0
	v_lshl_add_u32 v0, v1, 11, v0
	v_add_u32_e32 v0, s0, v0
	s_mov_b32 s0, 0x8000
	v_cmp_gt_i32_e32 vcc, s0, v0
	s_and_saveexec_b64 s[4:5], vcc
	v_readlane_b32 s16, v254, 24
	v_readlane_b32 s22, v254, 30
	v_readlane_b32 s23, v254, 31
	v_readlane_b32 s17, v254, 25
	v_readlane_b32 s18, v254, 26
	v_readlane_b32 s19, v254, 27
	v_readlane_b32 s20, v254, 28
	v_readlane_b32 s21, v254, 29
	s_cbranch_execz .LBB0_423
	s_lshl_b32 s6, s88, 9
	s_waitcnt lgkmcnt(0)
	v_ashrrev_i32_e32 v1, 31, v0
	v_mov_b64_e32 v[2:3], 0x10000
	s_ashr_i32 s7, s6, 31
	v_lshl_add_u64 v[2:3], v[0:1], 2, v[2:3]
	s_lshl_b64 s[8:9], s[6:7], 2
	v_lshlrev_b64 v[4:5], 7, v[0:1]
	s_lshl_b64 s[10:11], s[6:7], 7
	s_mov_b64 s[12:13], 0
	s_mov_b64 s[14:15], 0x3e900000
	s_mov_b64 s[16:17], 0x3e900040
	v_mov_b32_e32 v1, 0x358637bd
	s_mov_b32 s7, 0x800000
	s_movk_i32 s18, 0x7fff

; __device__ __forceinline__ unsigned xb_ld(unsigned* p)              { return __hip_atomic_load(p, __ATOMIC_RELAXED, __HIP_MEMORY_SCOPE_AGENT); }
; __device__ __forceinline__ unsigned xb_add(unsigned* p, unsigned v) { return __hip_atomic_fetch_add(p, v, __ATOMIC_RELAXED, __HIP_MEMORY_SCOPE_AGENT); }
; #define XB_SPIN(cond, bar) do { unsigned _sp = 0; while (cond) { __builtin_amdgcn_s_sleep(1); \
;     if ((++_sp & 255u) == 0u) { if (xb_ld(&(bar)[XB_TMO])) break; if (_sp > XB_SPIN_CAP) { atomicAdd(&(bar)[XB_TMO], 1u); break; } } } } while (0)
; __device__ __forceinline__ void xcd_barrier(const XcdBarrier& b) {
;     asm volatile("s_waitcnt vmcnt(0)" ::: "memory");
;     __syncthreads();
;     if (threadIdx.x == 0) {
;         unsigned* bar = b.bar;
;         __builtin_amdgcn_s_waitcnt(0);
;         unsigned nloc = b.st[0], nx = b.st[1];
;         if (nloc == 0u) { xcd_barrier_complete(bar, b.x, nloc, nx); b.st[0] = nloc; b.st[1] = nx; }
;         const unsigned old = xb_add(&bar[XB_XSUB(b.x)], 1u);
;         const unsigned gen = old / nloc;
;         if (old + 1u == (gen + 1u) * nloc) {
;             __builtin_amdgcn_fence(__ATOMIC_RELEASE, "agent");
;             asm volatile("s_waitcnt vmcnt(0)" ::: "memory");
;             const unsigned og = xb_add(&bar[XB_TOP], 1u);
;             const unsigned tg = og / nx;
;             if (og + 1u == (tg + 1u) * nx) xb_add(&bar[XB_TOPGEN], 1u);
;             else XB_SPIN(xb_ld(&bar[XB_TOPGEN]) == tg, bar);
;             __builtin_amdgcn_fence(__ATOMIC_ACQUIRE, "agent");
;             xb_add(&bar[XB_XGEN(b.x)], 1u);
;             asm volatile("s_waitcnt vmcnt(0)" ::: "memory");
;         } else {
;             XB_SPIN(xb_ld(&bar[XB_XGEN(b.x)]) == gen, bar);
;             __builtin_amdgcn_fence(__ATOMIC_ACQUIRE, "agent");
;             asm volatile("s_waitcnt vmcnt(0)" ::: "memory");
;         }
;     }
;     __syncthreads();
; }
.LBB0_424:
	s_cmp_gt_i32 s91, 5
	s_cselect_b64 s[0:1], -1, 0
	s_and_b64 s[2:3], s[2:3], s[0:1]
	s_andn2_b64 vcc, exec, s[2:3]
	s_cbranch_vccnz .LBB0_478
	s_waitcnt vmcnt(0)
	s_barrier

; DI int launder(int x) { asm volatile("" : "+v"(x)); return x; }
; DI void rs_phase(const float* PS, float* RS, int G, int blk) {
;     for (int row = blk * NTHREADS + launder((int)threadIdx.x); row < M; row += G * NTHREADS) {
;         const f32x4* p = (const f32x4*)(PS + (size_t)row * 32); float s = 0.f;
; #pragma unroll
;         for (int j = 0; j < 8; ++j) { const f32x4 v = p[j]; s += (v.x + v.y) + (v.z + v.w); }
;         RS[row] = rsqrtf(s * (1.f / 2048.f) + 1e-6f);
;     }
; }
.LBB0_875:
	s_cmp_lt_i32 s90, 10
	s_cselect_b64 s[0:1], -1, 0
	s_and_b64 s[2:3], s[0:1], s[2:3]
	s_andn2_b64 vcc, exec, s[2:3]
	s_cbranch_vccnz .LBB0_880
	v_mov_b32_e32 v0, v196
	s_and_b32 s0, s89, 7
	s_lshl_b32 s0, s0, 4
	s_bfe_u32 vcc_lo, s89, 0x30003
	s_add_i32 s0, s0, vcc_lo
	s_lshl_b32 s0, s0, 8
	v_lshrrev_b32_e32 v1, 8, v0
	v_and_b32_e32 v0, 0xff, v0
	v_lshl_add_u32 v0, v1, 11, v0
	v_add_u32_e32 v0, s0, v0
	s_mov_b32 s0, 0x8000
	v_cmp_gt_i32_e32 vcc, s0, v0
	s_and_saveexec_b64 s[4:5], vcc
	v_readlane_b32 s16, v254, 24
	v_readlane_b32 s22, v254, 30
	v_readlane_b32 s23, v254, 31
	v_readlane_b32 s17, v254, 25
	v_readlane_b32 s18, v254, 26
	v_readlane_b32 s19, v254, 27
	v_readlane_b32 s20, v254, 28
	v_readlane_b32 s21, v254, 29
	s_cbranch_execz .LBB0_879
	s_lshl_b32 s6, s88, 9
	s_waitcnt lgkmcnt(0)
	v_ashrrev_i32_e32 v1, 31, v0
	v_mov_b64_e32 v[2:3], 0x10000
	s_ashr_i32 s7, s6, 31
	v_lshl_add_u64 v[2:3], v[0:1], 2, v[2:3]
	s_lshl_b64 s[8:9], s[6:7], 2
	v_lshlrev_b64 v[4:5], 7, v[0:1]
	s_lshl_b64 s[10:11], s[6:7], 7
	s_mov_b64 s[12:13], 0
	s_mov_b64 s[14:15], 0x3e900000
	s_mov_b64 s[16:17], 0x3e900040
	v_mov_b32_e32 v1, 0x358637bd
	s_mov_b32 s7, 0x800000
	s_movk_i32 s18, 0x7fff

; __device__ __forceinline__ unsigned xb_ld(unsigned* p)              { return __hip_atomic_load(p, __ATOMIC_RELAXED, __HIP_MEMORY_SCOPE_AGENT); }
; __device__ __forceinline__ unsigned xb_add(unsigned* p, unsigned v) { return __hip_atomic_fetch_add(p, v, __ATOMIC_RELAXED, __HIP_MEMORY_SCOPE_AGENT); }
; #define XB_SPIN(cond, bar) do { unsigned _sp = 0; while (cond) { __builtin_amdgcn_s_sleep(1); \
;     if ((++_sp & 255u) == 0u) { if (xb_ld(&(bar)[XB_TMO])) break; if (_sp > XB_SPIN_CAP) { atomicAdd(&(bar)[XB_TMO], 1u); break; } } } } while (0)
; __device__ __forceinline__ void xcd_barrier(const XcdBarrier& b) {
;     asm volatile("s_waitcnt vmcnt(0)" ::: "memory");
;     __syncthreads();
;     if (threadIdx.x == 0) {
;         unsigned* bar = b.bar;
;         __builtin_amdgcn_s_waitcnt(0);
;         unsigned nloc = b.st[0], nx = b.st[1];
;         if (nloc == 0u) { xcd_barrier_complete(bar, b.x, nloc, nx); b.st[0] = nloc; b.st[1] = nx; }
;         const unsigned old = xb_add(&bar[XB_XSUB(b.x)], 1u);
;         const unsigned gen = old / nloc;
;         if (old + 1u == (gen + 1u) * nloc) {
;             __builtin_amdgcn_fence(__ATOMIC_RELEASE, "agent");
;             asm volatile("s_waitcnt vmcnt(0)" ::: "memory");
;             const unsigned og = xb_add(&bar[XB_TOP], 1u);
;             const unsigned tg = og / nx;
;             if (og + 1u == (tg + 1u) * nx) xb_add(&bar[XB_TOPGEN], 1u);
;             else XB_SPIN(xb_ld(&bar[XB_TOPGEN]) == tg, bar);
;             __builtin_amdgcn_fence(__ATOMIC_ACQUIRE, "agent");
;             xb_add(&bar[XB_XGEN(b.x)], 1u);
;             asm volatile("s_waitcnt vmcnt(0)" ::: "memory");
;         } else {
;             XB_SPIN(xb_ld(&bar[XB_XGEN(b.x)]) == gen, bar);
;             __builtin_amdgcn_fence(__ATOMIC_ACQUIRE, "agent");
;             asm volatile("s_waitcnt vmcnt(0)" ::: "memory");
;         }
;     }
;     __syncthreads();
; }
.LBB0_880:
	s_cmp_gt_i32 s91, 10
	s_cselect_b64 s[0:1], -1, 0
	s_and_b64 s[2:3], s[2:3], s[0:1]
	s_andn2_b64 vcc, exec, s[2:3]
	s_cbranch_vccnz .LBB0_934
	s_waitcnt vmcnt(0)
	s_barrier

; DI int launder(int x) { asm volatile("" : "+v"(x)); return x; }
; DI void rs_phase(const float* PS, float* RS, int G, int blk) {
;     for (int row = blk * NTHREADS + launder((int)threadIdx.x); row < M; row += G * NTHREADS) {
;         const f32x4* p = (const f32x4*)(PS + (size_t)row * 32); float s = 0.f;
; #pragma unroll
;         for (int j = 0; j < 8; ++j) { const f32x4 v = p[j]; s += (v.x + v.y) + (v.z + v.w); }
;         RS[row] = rsqrtf(s * (1.f / 2048.f) + 1e-6f);
;     }
; }
.LBB0_1292:
	s_cmp_lt_i32 s90, 14
	s_cselect_b64 s[0:1], -1, 0
	s_and_b64 s[2:3], s[0:1], s[2:3]
	s_andn2_b64 vcc, exec, s[2:3]
	s_cbranch_vccnz .LBB0_1297
	v_mov_b32_e32 v0, v196
	s_and_b32 s0, s89, 7
	s_lshl_b32 s0, s0, 4
	s_bfe_u32 vcc_lo, s89, 0x30003
	s_add_i32 s0, s0, vcc_lo
	s_lshl_b32 s0, s0, 8
	v_lshrrev_b32_e32 v1, 8, v0
	v_and_b32_e32 v0, 0xff, v0
	v_lshl_add_u32 v0, v1, 11, v0
	v_add_u32_e32 v0, s0, v0
	s_mov_b32 s0, 0x8000
	v_cmp_gt_i32_e32 vcc, s0, v0
	s_and_saveexec_b64 s[4:5], vcc
	s_cbranch_execz .LBB0_1296
	s_lshl_b32 s6, s88, 9
	s_waitcnt lgkmcnt(0)
	v_ashrrev_i32_e32 v1, 31, v0
	v_mov_b64_e32 v[2:3], 0x10000
	s_ashr_i32 s7, s6, 31
	v_lshl_add_u64 v[2:3], v[0:1], 2, v[2:3]
	s_lshl_b64 s[8:9], s[6:7], 2
	v_lshlrev_b64 v[4:5], 7, v[0:1]
	s_lshl_b64 s[10:11], s[6:7], 7
	s_mov_b64 s[12:13], 0
	s_mov_b64 s[14:15], 0x3e900000
	s_mov_b64 s[16:17], 0x3e900040
	v_mov_b32_e32 v1, 0x358637bd
	s_mov_b32 s7, 0x800000
	s_movk_i32 s18, 0x7fff

; __device__ __forceinline__ unsigned xb_ld(unsigned* p)              { return __hip_atomic_load(p, __ATOMIC_RELAXED, __HIP_MEMORY_SCOPE_AGENT); }
; __device__ __forceinline__ unsigned xb_add(unsigned* p, unsigned v) { return __hip_atomic_fetch_add(p, v, __ATOMIC_RELAXED, __HIP_MEMORY_SCOPE_AGENT); }
; #define XB_SPIN(cond, bar) do { unsigned _sp = 0; while (cond) { __builtin_amdgcn_s_sleep(1); \
;     if ((++_sp & 255u) == 0u) { if (xb_ld(&(bar)[XB_TMO])) break; if (_sp > XB_SPIN_CAP) { atomicAdd(&(bar)[XB_TMO], 1u); break; } } } } while (0)
; __device__ __forceinline__ void xcd_barrier(const XcdBarrier& b) {
;     asm volatile("s_waitcnt vmcnt(0)" ::: "memory");
;     __syncthreads();
;     if (threadIdx.x == 0) {
;         unsigned* bar = b.bar;
;         __builtin_amdgcn_s_waitcnt(0);
;         unsigned nloc = b.st[0], nx = b.st[1];
;         if (nloc == 0u) { xcd_barrier_complete(bar, b.x, nloc, nx); b.st[0] = nloc; b.st[1] = nx; }
;         const unsigned old = xb_add(&bar[XB_XSUB(b.x)], 1u);
;         const unsigned gen = old / nloc;
;         if (old + 1u == (gen + 1u) * nloc) {
;             __builtin_amdgcn_fence(__ATOMIC_RELEASE, "agent");
;             asm volatile("s_waitcnt vmcnt(0)" ::: "memory");
;             const unsigned og = xb_add(&bar[XB_TOP], 1u);
;             const unsigned tg = og / nx;
;             if (og + 1u == (tg + 1u) * nx) xb_add(&bar[XB_TOPGEN], 1u);
;             else XB_SPIN(xb_ld(&bar[XB_TOPGEN]) == tg, bar);
;             __builtin_amdgcn_fence(__ATOMIC_ACQUIRE, "agent");
;             xb_add(&bar[XB_XGEN(b.x)], 1u);
;             asm volatile("s_waitcnt vmcnt(0)" ::: "memory");
;         } else {
;             XB_SPIN(xb_ld(&bar[XB_XGEN(b.x)]) == gen, bar);
;             __builtin_amdgcn_fence(__ATOMIC_ACQUIRE, "agent");
;             asm volatile("s_waitcnt vmcnt(0)" ::: "memory");
;         }
;     }
;     __syncthreads();
; }
.LBB0_1297:
	s_cmp_gt_i32 s91, 14
	s_cselect_b64 s[0:1], -1, 0
	s_and_b64 s[2:3], s[2:3], s[0:1]
	s_andn2_b64 vcc, exec, s[2:3]
	s_cbranch_vccnz .LBB0_1351
	s_waitcnt vmcnt(0)
	s_barrier
